# phase0 weight transposer (gain variants): all 16+16 loads of a tile issued before one wait instead of a round trip per element
# speedup vs baseline: 1.0065x; 1.0065x over previous
; __device__ __forceinline__ void wt_tile(unsigned char* smem, const float* src, int K, int N, const float* gain, bf16_t* dst, int perm, int t) {
;     ...
;   __syncthreads();
; #pragma unroll 4
;   for (int i = 0; i < 16; ++i) {
;     const int kk = (tid >> 6) + 4 * i;
;     float v = src[(size_t)(k0 + kk) * N + sc];
;     if (gain) v *= gain[k0 + kk];
;     tl[kk * 65 + rr] = v;
;   }
.LBB0_5:
	v_mad_i64_i32 v[98:99], s[24:25], v10, s18, v[4:5]
	global_load_dword v64, v[98:99], off
	v_add_u32_e32 v96, 4, v10
	v_mad_i64_i32 v[98:99], s[24:25], v96, s18, v[4:5]
	global_load_dword v65, v[98:99], off
	v_add_u32_e32 v96, 8, v10
	v_mad_i64_i32 v[98:99], s[24:25], v96, s18, v[4:5]
	global_load_dword v66, v[98:99], off
	v_add_u32_e32 v96, 12, v10
	v_mad_i64_i32 v[98:99], s[24:25], v96, s18, v[4:5]
	global_load_dword v67, v[98:99], off
	v_add_u32_e32 v96, 16, v10
	v_mad_i64_i32 v[98:99], s[24:25], v96, s18, v[4:5]
	global_load_dword v68, v[98:99], off
	v_add_u32_e32 v96, 20, v10
	v_mad_i64_i32 v[98:99], s[24:25], v96, s18, v[4:5]
	global_load_dword v69, v[98:99], off
	v_add_u32_e32 v96, 24, v10
	v_mad_i64_i32 v[98:99], s[24:25], v96, s18, v[4:5]
	global_load_dword v70, v[98:99], off
	v_add_u32_e32 v96, 28, v10
	v_mad_i64_i32 v[98:99], s[24:25], v96, s18, v[4:5]
	global_load_dword v71, v[98:99], off
	v_add_u32_e32 v96, 32, v10
	v_mad_i64_i32 v[98:99], s[24:25], v96, s18, v[4:5]
	global_load_dword v72, v[98:99], off
	v_add_u32_e32 v96, 36, v10
	v_mad_i64_i32 v[98:99], s[24:25], v96, s18, v[4:5]
	global_load_dword v73, v[98:99], off
	v_add_u32_e32 v96, 40, v10
	v_mad_i64_i32 v[98:99], s[24:25], v96, s18, v[4:5]
	global_load_dword v74, v[98:99], off
	v_add_u32_e32 v96, 44, v10
	v_mad_i64_i32 v[98:99], s[24:25], v96, s18, v[4:5]
	global_load_dword v75, v[98:99], off
	v_add_u32_e32 v96, 48, v10
	v_mad_i64_i32 v[98:99], s[24:25], v96, s18, v[4:5]
	global_load_dword v76, v[98:99], off
	v_add_u32_e32 v96, 52, v10
	v_mad_i64_i32 v[98:99], s[24:25], v96, s18, v[4:5]
	global_load_dword v77, v[98:99], off
	v_add_u32_e32 v96, 56, v10
	v_mad_i64_i32 v[98:99], s[24:25], v96, s18, v[4:5]
	global_load_dword v78, v[98:99], off
	v_add_u32_e32 v96, 60, v10
	v_mad_i64_i32 v[98:99], s[24:25], v96, s18, v[4:5]
	global_load_dword v79, v[98:99], off
	s_and_b64 vcc, exec, s[4:5]
	s_cbranch_vccnz .Lwta_nogain
	global_load_dword v80, v[6:7], off offset:-32
	global_load_dword v81, v[6:7], off offset:-16
	global_load_dword v82, v[6:7], off
	global_load_dword v83, v[6:7], off offset:16
	global_load_dword v84, v[6:7], off offset:32
	global_load_dword v85, v[6:7], off offset:48
	global_load_dword v86, v[6:7], off offset:64
	global_load_dword v87, v[6:7], off offset:80
	global_load_dword v88, v[6:7], off offset:96
	global_load_dword v89, v[6:7], off offset:112
	global_load_dword v90, v[6:7], off offset:128
	global_load_dword v91, v[6:7], off offset:144
	global_load_dword v92, v[6:7], off offset:160
	global_load_dword v93, v[6:7], off offset:176
	global_load_dword v94, v[6:7], off offset:192
	global_load_dword v95, v[6:7], off offset:208
	s_waitcnt vmcnt(0)
	v_mul_f32_e32 v64, v64, v80
	v_mul_f32_e32 v65, v65, v81
	v_mul_f32_e32 v66, v66, v82
	v_mul_f32_e32 v67, v67, v83
	v_mul_f32_e32 v68, v68, v84
	v_mul_f32_e32 v69, v69, v85
	v_mul_f32_e32 v70, v70, v86
	v_mul_f32_e32 v71, v71, v87
	v_mul_f32_e32 v72, v72, v88
	v_mul_f32_e32 v73, v73, v89
	v_mul_f32_e32 v74, v74, v90
	v_mul_f32_e32 v75, v75, v91
	v_mul_f32_e32 v76, v76, v92
	v_mul_f32_e32 v77, v77, v93
	v_mul_f32_e32 v78, v78, v94
	v_mul_f32_e32 v79, v79, v95
.Lwta_nogain:
	s_waitcnt vmcnt(0)
	ds_write_b32 v2, v64
	ds_write_b32 v2, v65 offset:1040
	ds_write_b32 v2, v66 offset:2080
	ds_write_b32 v2, v67 offset:3120
	ds_write_b32 v2, v68 offset:4160
	ds_write_b32 v2, v69 offset:5200
	ds_write_b32 v2, v70 offset:6240
	ds_write_b32 v2, v71 offset:7280
	ds_write_b32 v2, v72 offset:8320
	ds_write_b32 v2, v73 offset:9360
	ds_write_b32 v2, v74 offset:10400
	ds_write_b32 v2, v75 offset:11440
	ds_write_b32 v2, v76 offset:12480
	ds_write_b32 v2, v77 offset:13520
	ds_write_b32 v2, v78 offset:14560
	ds_write_b32 v2, v79 offset:15600
	s_branch .LBB0_2

; __device__ __forceinline__ void wt_tile(unsigned char* smem, const float* src, int K, int N, const float* gain, bf16_t* dst, int perm, int t) {
;     ...
;   for (int i = 0; i < 16; ++i) {
;     const int kk = (tid >> 6) + 4 * i;
;     float v = src[(size_t)(k0 + kk) * N + sc];
;     if (gain) v *= gain[k0 + kk];
;     tl[kk * 65 + rr] = v;
;   }
.LBB0_48:
	v_mov_b32_e32 v96, v10
	v_ashrrev_i32_e32 v97, 31, v96
	v_lshlrev_b64 v[98:99], 12, v[96:97]
	v_lshl_add_u64 v[98:99], v[4:5], 0, v[98:99]
	global_load_dword v64, v[98:99], off
	v_add_u32_e32 v96, 4, v10
	v_ashrrev_i32_e32 v97, 31, v96
	v_lshlrev_b64 v[98:99], 12, v[96:97]
	v_lshl_add_u64 v[98:99], v[4:5], 0, v[98:99]
	global_load_dword v65, v[98:99], off
	v_add_u32_e32 v96, 8, v10
	v_ashrrev_i32_e32 v97, 31, v96
	v_lshlrev_b64 v[98:99], 12, v[96:97]
	v_lshl_add_u64 v[98:99], v[4:5], 0, v[98:99]
	global_load_dword v66, v[98:99], off
	v_add_u32_e32 v96, 12, v10
	v_ashrrev_i32_e32 v97, 31, v96
	v_lshlrev_b64 v[98:99], 12, v[96:97]
	v_lshl_add_u64 v[98:99], v[4:5], 0, v[98:99]
	global_load_dword v67, v[98:99], off
	v_add_u32_e32 v96, 16, v10
	v_ashrrev_i32_e32 v97, 31, v96
	v_lshlrev_b64 v[98:99], 12, v[96:97]
	v_lshl_add_u64 v[98:99], v[4:5], 0, v[98:99]
	global_load_dword v68, v[98:99], off
	v_add_u32_e32 v96, 20, v10
	v_ashrrev_i32_e32 v97, 31, v96
	v_lshlrev_b64 v[98:99], 12, v[96:97]
	v_lshl_add_u64 v[98:99], v[4:5], 0, v[98:99]
	global_load_dword v69, v[98:99], off
	v_add_u32_e32 v96, 24, v10
	v_ashrrev_i32_e32 v97, 31, v96
	v_lshlrev_b64 v[98:99], 12, v[96:97]
	v_lshl_add_u64 v[98:99], v[4:5], 0, v[98:99]
	global_load_dword v70, v[98:99], off
	v_add_u32_e32 v96, 28, v10
	v_ashrrev_i32_e32 v97, 31, v96
	v_lshlrev_b64 v[98:99], 12, v[96:97]
	v_lshl_add_u64 v[98:99], v[4:5], 0, v[98:99]
	global_load_dword v71, v[98:99], off
	v_add_u32_e32 v96, 32, v10
	v_ashrrev_i32_e32 v97, 31, v96
	v_lshlrev_b64 v[98:99], 12, v[96:97]
	v_lshl_add_u64 v[98:99], v[4:5], 0, v[98:99]
	global_load_dword v72, v[98:99], off
	v_add_u32_e32 v96, 36, v10
	v_ashrrev_i32_e32 v97, 31, v96
	v_lshlrev_b64 v[98:99], 12, v[96:97]
	v_lshl_add_u64 v[98:99], v[4:5], 0, v[98:99]
	global_load_dword v73, v[98:99], off
	v_add_u32_e32 v96, 40, v10
	v_ashrrev_i32_e32 v97, 31, v96
	v_lshlrev_b64 v[98:99], 12, v[96:97]
	v_lshl_add_u64 v[98:99], v[4:5], 0, v[98:99]
	global_load_dword v74, v[98:99], off
	v_add_u32_e32 v96, 44, v10
	v_ashrrev_i32_e32 v97, 31, v96
	v_lshlrev_b64 v[98:99], 12, v[96:97]
	v_lshl_add_u64 v[98:99], v[4:5], 0, v[98:99]
	global_load_dword v75, v[98:99], off
	v_add_u32_e32 v96, 48, v10
	v_ashrrev_i32_e32 v97, 31, v96
	v_lshlrev_b64 v[98:99], 12, v[96:97]
	v_lshl_add_u64 v[98:99], v[4:5], 0, v[98:99]
	global_load_dword v76, v[98:99], off
	v_add_u32_e32 v96, 52, v10
	v_ashrrev_i32_e32 v97, 31, v96
	v_lshlrev_b64 v[98:99], 12, v[96:97]
	v_lshl_add_u64 v[98:99], v[4:5], 0, v[98:99]
	global_load_dword v77, v[98:99], off
	v_add_u32_e32 v96, 56, v10
	v_ashrrev_i32_e32 v97, 31, v96
	v_lshlrev_b64 v[98:99], 12, v[96:97]
	v_lshl_add_u64 v[98:99], v[4:5], 0, v[98:99]
	global_load_dword v78, v[98:99], off
	v_add_u32_e32 v96, 60, v10
	v_ashrrev_i32_e32 v97, 31, v96
	v_lshlrev_b64 v[98:99], 12, v[96:97]
	v_lshl_add_u64 v[98:99], v[4:5], 0, v[98:99]
	global_load_dword v79, v[98:99], off
	s_and_b64 vcc, exec, s[4:5]
	s_cbranch_vccnz .Lwtb_nogain
	global_load_dword v80, v[6:7], off offset:-32
	global_load_dword v81, v[6:7], off offset:-16
	global_load_dword v82, v[6:7], off
	global_load_dword v83, v[6:7], off offset:16
	global_load_dword v84, v[6:7], off offset:32
	global_load_dword v85, v[6:7], off offset:48
	global_load_dword v86, v[6:7], off offset:64
	global_load_dword v87, v[6:7], off offset:80
	global_load_dword v88, v[6:7], off offset:96
	global_load_dword v89, v[6:7], off offset:112
	global_load_dword v90, v[6:7], off offset:128
	global_load_dword v91, v[6:7], off offset:144
	global_load_dword v92, v[6:7], off offset:160
	global_load_dword v93, v[6:7], off offset:176
	global_load_dword v94, v[6:7], off offset:192
	global_load_dword v95, v[6:7], off offset:208
	s_waitcnt vmcnt(0)
	v_mul_f32_e32 v64, v64, v80
	v_mul_f32_e32 v65, v65, v81
	v_mul_f32_e32 v66, v66, v82
	v_mul_f32_e32 v67, v67, v83
	v_mul_f32_e32 v68, v68, v84
	v_mul_f32_e32 v69, v69, v85
	v_mul_f32_e32 v70, v70, v86
	v_mul_f32_e32 v71, v71, v87
	v_mul_f32_e32 v72, v72, v88
	v_mul_f32_e32 v73, v73, v89
	v_mul_f32_e32 v74, v74, v90
	v_mul_f32_e32 v75, v75, v91
	v_mul_f32_e32 v76, v76, v92
	v_mul_f32_e32 v77, v77, v93
	v_mul_f32_e32 v78, v78, v94
	v_mul_f32_e32 v79, v79, v95

; __device__ __forceinline__ void wt_tile(unsigned char* smem, const float* src, int K, int N, const float* gain, bf16_t* dst, int perm, int t) {
;     ...
;   for (int i = 0; i < 16; ++i) {
;     const int kk = (tid >> 6) + 4 * i;
;     float v = src[(size_t)(k0 + kk) * N + sc];
;     if (gain) v *= gain[k0 + kk];
;     tl[kk * 65 + rr] = v;
;   }
.LBB0_61:
	v_mov_b32_e32 v96, v10
	v_ashrrev_i32_e32 v97, 31, v96
	v_lshlrev_b64 v[98:99], 13, v[96:97]
	v_lshl_add_u64 v[98:99], v[4:5], 0, v[98:99]
	global_load_dword v64, v[98:99], off
	v_add_u32_e32 v96, 4, v10
	v_ashrrev_i32_e32 v97, 31, v96
	v_lshlrev_b64 v[98:99], 13, v[96:97]
	v_lshl_add_u64 v[98:99], v[4:5], 0, v[98:99]
	global_load_dword v65, v[98:99], off
	v_add_u32_e32 v96, 8, v10
	v_ashrrev_i32_e32 v97, 31, v96
	v_lshlrev_b64 v[98:99], 13, v[96:97]
	v_lshl_add_u64 v[98:99], v[4:5], 0, v[98:99]
	global_load_dword v66, v[98:99], off
	v_add_u32_e32 v96, 12, v10
	v_ashrrev_i32_e32 v97, 31, v96
	v_lshlrev_b64 v[98:99], 13, v[96:97]
	v_lshl_add_u64 v[98:99], v[4:5], 0, v[98:99]
	global_load_dword v67, v[98:99], off
	v_add_u32_e32 v96, 16, v10
	v_ashrrev_i32_e32 v97, 31, v96
	v_lshlrev_b64 v[98:99], 13, v[96:97]
	v_lshl_add_u64 v[98:99], v[4:5], 0, v[98:99]
	global_load_dword v68, v[98:99], off
	v_add_u32_e32 v96, 20, v10
	v_ashrrev_i32_e32 v97, 31, v96
	v_lshlrev_b64 v[98:99], 13, v[96:97]
	v_lshl_add_u64 v[98:99], v[4:5], 0, v[98:99]
	global_load_dword v69, v[98:99], off
	v_add_u32_e32 v96, 24, v10
	v_ashrrev_i32_e32 v97, 31, v96
	v_lshlrev_b64 v[98:99], 13, v[96:97]
	v_lshl_add_u64 v[98:99], v[4:5], 0, v[98:99]
	global_load_dword v70, v[98:99], off
	v_add_u32_e32 v96, 28, v10
	v_ashrrev_i32_e32 v97, 31, v96
	v_lshlrev_b64 v[98:99], 13, v[96:97]
	v_lshl_add_u64 v[98:99], v[4:5], 0, v[98:99]
	global_load_dword v71, v[98:99], off
	v_add_u32_e32 v96, 32, v10
	v_ashrrev_i32_e32 v97, 31, v96
	v_lshlrev_b64 v[98:99], 13, v[96:97]
	v_lshl_add_u64 v[98:99], v[4:5], 0, v[98:99]
	global_load_dword v72, v[98:99], off
	v_add_u32_e32 v96, 36, v10
	v_ashrrev_i32_e32 v97, 31, v96
	v_lshlrev_b64 v[98:99], 13, v[96:97]
	v_lshl_add_u64 v[98:99], v[4:5], 0, v[98:99]
	global_load_dword v73, v[98:99], off
	v_add_u32_e32 v96, 40, v10
	v_ashrrev_i32_e32 v97, 31, v96
	v_lshlrev_b64 v[98:99], 13, v[96:97]
	v_lshl_add_u64 v[98:99], v[4:5], 0, v[98:99]
	global_load_dword v74, v[98:99], off
	v_add_u32_e32 v96, 44, v10
	v_ashrrev_i32_e32 v97, 31, v96
	v_lshlrev_b64 v[98:99], 13, v[96:97]
	v_lshl_add_u64 v[98:99], v[4:5], 0, v[98:99]
	global_load_dword v75, v[98:99], off
	v_add_u32_e32 v96, 48, v10
	v_ashrrev_i32_e32 v97, 31, v96
	v_lshlrev_b64 v[98:99], 13, v[96:97]
	v_lshl_add_u64 v[98:99], v[4:5], 0, v[98:99]
	global_load_dword v76, v[98:99], off
	v_add_u32_e32 v96, 52, v10
	v_ashrrev_i32_e32 v97, 31, v96
	v_lshlrev_b64 v[98:99], 13, v[96:97]
	v_lshl_add_u64 v[98:99], v[4:5], 0, v[98:99]
	global_load_dword v77, v[98:99], off
	v_add_u32_e32 v96, 56, v10
	v_ashrrev_i32_e32 v97, 31, v96
	v_lshlrev_b64 v[98:99], 13, v[96:97]
	v_lshl_add_u64 v[98:99], v[4:5], 0, v[98:99]
	global_load_dword v78, v[98:99], off
	v_add_u32_e32 v96, 60, v10
	v_ashrrev_i32_e32 v97, 31, v96
	v_lshlrev_b64 v[98:99], 13, v[96:97]
	v_lshl_add_u64 v[98:99], v[4:5], 0, v[98:99]
	global_load_dword v79, v[98:99], off
	s_and_b64 vcc, exec, s[8:9]
	s_cbranch_vccnz .Lwtc_nogain
	global_load_dword v80, v[6:7], off offset:-32
	global_load_dword v81, v[6:7], off offset:-16
	global_load_dword v82, v[6:7], off
	global_load_dword v83, v[6:7], off offset:16
	global_load_dword v84, v[6:7], off offset:32
	global_load_dword v85, v[6:7], off offset:48
	global_load_dword v86, v[6:7], off offset:64
	global_load_dword v87, v[6:7], off offset:80
	global_load_dword v88, v[6:7], off offset:96
	global_load_dword v89, v[6:7], off offset:112
	global_load_dword v90, v[6:7], off offset:128
	global_load_dword v91, v[6:7], off offset:144
	global_load_dword v92, v[6:7], off offset:160
	global_load_dword v93, v[6:7], off offset:176
	global_load_dword v94, v[6:7], off offset:192
	global_load_dword v95, v[6:7], off offset:208
	s_waitcnt vmcnt(0)
	v_mul_f32_e32 v64, v64, v80
	v_mul_f32_e32 v65, v65, v81
	v_mul_f32_e32 v66, v66, v82
	v_mul_f32_e32 v67, v67, v83
	v_mul_f32_e32 v68, v68, v84
	v_mul_f32_e32 v69, v69, v85
	v_mul_f32_e32 v70, v70, v86
	v_mul_f32_e32 v71, v71, v87
	v_mul_f32_e32 v72, v72, v88
	v_mul_f32_e32 v73, v73, v89
	v_mul_f32_e32 v74, v74, v90
	v_mul_f32_e32 v75, v75, v91
	v_mul_f32_e32 v76, v76, v92
	v_mul_f32_e32 v77, v77, v93
	v_mul_f32_e32 v78, v78, v94
	v_mul_f32_e32 v79, v79, v95

; __device__ __forceinline__ void wt_tile(unsigned char* smem, const float* src, int K, int N, const float* gain, bf16_t* dst, int perm, int t) {
;     ...
;   if (perm) { const int T = R >> 8, within = R & 255, wc = within >> 7, n = (within & 127) >> 4, i = within & 15; sc = (n & 1) * DFF + 128 * T + 64 * wc + 16 * (n >> 1) + i; }
;     ...
;   for (int i = 0; i < 16; ++i) {
;     const int kk = (tid >> 6) + 4 * i;
;     float v = src[(size_t)(k0 + kk) * N + sc];
;     if (gain) v *= gain[k0 + kk];
;     tl[kk * 65 + rr] = v;
;   }
.LBB0_83:
	v_mad_i64_i32 v[98:99], s[60:61], v11, s56, v[4:5]
	global_load_dword v64, v[98:99], off
	v_add_u32_e32 v96, 4, v11
	v_mad_i64_i32 v[98:99], s[60:61], v96, s56, v[4:5]
	global_load_dword v65, v[98:99], off
	v_add_u32_e32 v96, 8, v11
	v_mad_i64_i32 v[98:99], s[60:61], v96, s56, v[4:5]
	global_load_dword v66, v[98:99], off
	v_add_u32_e32 v96, 12, v11
	v_mad_i64_i32 v[98:99], s[60:61], v96, s56, v[4:5]
	global_load_dword v67, v[98:99], off
	v_add_u32_e32 v96, 16, v11
	v_mad_i64_i32 v[98:99], s[60:61], v96, s56, v[4:5]
	global_load_dword v68, v[98:99], off
	v_add_u32_e32 v96, 20, v11
	v_mad_i64_i32 v[98:99], s[60:61], v96, s56, v[4:5]
	global_load_dword v69, v[98:99], off
	v_add_u32_e32 v96, 24, v11
	v_mad_i64_i32 v[98:99], s[60:61], v96, s56, v[4:5]
	global_load_dword v70, v[98:99], off
	v_add_u32_e32 v96, 28, v11
	v_mad_i64_i32 v[98:99], s[60:61], v96, s56, v[4:5]
	global_load_dword v71, v[98:99], off
	v_add_u32_e32 v96, 32, v11
	v_mad_i64_i32 v[98:99], s[60:61], v96, s56, v[4:5]
	global_load_dword v72, v[98:99], off
	v_add_u32_e32 v96, 36, v11
	v_mad_i64_i32 v[98:99], s[60:61], v96, s56, v[4:5]
	global_load_dword v73, v[98:99], off
	v_add_u32_e32 v96, 40, v11
	v_mad_i64_i32 v[98:99], s[60:61], v96, s56, v[4:5]
	global_load_dword v74, v[98:99], off
	v_add_u32_e32 v96, 44, v11
	v_mad_i64_i32 v[98:99], s[60:61], v96, s56, v[4:5]
	global_load_dword v75, v[98:99], off
	v_add_u32_e32 v96, 48, v11
	v_mad_i64_i32 v[98:99], s[60:61], v96, s56, v[4:5]
	global_load_dword v76, v[98:99], off
	v_add_u32_e32 v96, 52, v11
	v_mad_i64_i32 v[98:99], s[60:61], v96, s56, v[4:5]
	global_load_dword v77, v[98:99], off
	v_add_u32_e32 v96, 56, v11
	v_mad_i64_i32 v[98:99], s[60:61], v96, s56, v[4:5]
	global_load_dword v78, v[98:99], off
	v_add_u32_e32 v96, 60, v11
	v_mad_i64_i32 v[98:99], s[60:61], v96, s56, v[4:5]
	global_load_dword v79, v[98:99], off
	s_andn2_b64 vcc, exec, s[34:35]
	s_cbranch_vccnz .Lwtd_nogain
	global_load_dword v80, v[6:7], off offset:-32
	global_load_dword v81, v[6:7], off offset:-16
	global_load_dword v82, v[6:7], off
	global_load_dword v83, v[6:7], off offset:16
	global_load_dword v84, v[6:7], off offset:32
	global_load_dword v85, v[6:7], off offset:48
	global_load_dword v86, v[6:7], off offset:64
	global_load_dword v87, v[6:7], off offset:80
	global_load_dword v88, v[6:7], off offset:96
	global_load_dword v89, v[6:7], off offset:112
	global_load_dword v90, v[6:7], off offset:128
	global_load_dword v91, v[6:7], off offset:144
	global_load_dword v92, v[6:7], off offset:160
	global_load_dword v93, v[6:7], off offset:176
	global_load_dword v94, v[6:7], off offset:192
	global_load_dword v95, v[6:7], off offset:208
	s_waitcnt vmcnt(0)
	v_mul_f32_e32 v64, v64, v80
	v_mul_f32_e32 v65, v65, v81
	v_mul_f32_e32 v66, v66, v82
	v_mul_f32_e32 v67, v67, v83
	v_mul_f32_e32 v68, v68, v84
	v_mul_f32_e32 v69, v69, v85
	v_mul_f32_e32 v70, v70, v86
	v_mul_f32_e32 v71, v71, v87
	v_mul_f32_e32 v72, v72, v88
	v_mul_f32_e32 v73, v73, v89
	v_mul_f32_e32 v74, v74, v90
	v_mul_f32_e32 v75, v75, v91
	v_mul_f32_e32 v76, v76, v92
	v_mul_f32_e32 v77, v77, v93
	v_mul_f32_e32 v78, v78, v94
	v_mul_f32_e32 v79, v79, v95
.Lwtd_nogain:
	s_waitcnt vmcnt(0)
	ds_write_b32 v10, v64
	ds_write_b32 v10, v65 offset:1040
	ds_write_b32 v10, v66 offset:2080
	ds_write_b32 v10, v67 offset:3120
	ds_write_b32 v10, v68 offset:4160
	ds_write_b32 v10, v69 offset:5200
	ds_write_b32 v10, v70 offset:6240
	ds_write_b32 v10, v71 offset:7280
	ds_write_b32 v10, v72 offset:8320
	ds_write_b32 v10, v73 offset:9360
	ds_write_b32 v10, v74 offset:10400
	ds_write_b32 v10, v75 offset:11440
	ds_write_b32 v10, v76 offset:12480
	ds_write_b32 v10, v77 offset:13520
	ds_write_b32 v10, v78 offset:14560
	ds_write_b32 v10, v79 offset:15600
	s_branch .LBB0_80
